# SGU preamble: 32 W_s f32 loads issued in two batches of 16 instead of 16 serial load-pair+wait steps
# baseline (speedup 1.0000x reference)
; __device__ __forceinline__ unsigned cvt_pk_bf16(float lo, float hi) { unsigned r; asm volatile("v_cvt_pk_bf16_f32 %0, %1, %2" : "=v"(r) : "v"(lo), "v"(hi)); return r; }
; #define LAS __attribute__((address_space(3)))
; __device__ __forceinline__ void sgu_units(LAS unsigned char* lds, const bf16* UB, const bf16* GVT, const bf16* GVTc, bf16* MIX, const float* wsgu, const float* bsgu, const float* gsgu, const float* gmix,
;                                           int nchunks, int G, int bid, int tid) {
;     ...
;     const int wave = __builtin_amdgcn_readfirstlane(tid >> 6), lane = tid & 63, hd = wave >> 1, ph = wave & 1, c = lane & 31, h2 = lane >> 5;
;     LAS float* rq = (LAS float*)lds + wave * 128;
;     bf16x8 bfr[2][8];
; #pragma unroll
;     for (int ps = 0; ps < 2; ++ps)
; #pragma unroll
;         for (int ks = 0; ks < 8; ++ks) { const float* wp = wsgu + ((size_t)(hd * 128 + ph * 64 + ps * 32 + c)) * 128 + ks * 16 + h2 * 8; const f32x4 w0 = *(const f32x4*)wp, w1 = *(const f32x4*)(wp + 4);
;             v4u w; w.x = cvt_pk_bf16(w0[0], w0[1]); w.y = cvt_pk_bf16(w0[2], w0[3]); w.z = cvt_pk_bf16(w1[0], w1[1]); w.w = cvt_pk_bf16(w1[2], w1[3]); bfr[ps][ks] = __builtin_bit_cast(bf16x8, w); }
;     for (int L = bid; L < nchunks; L += G) {
.LBB0_339:
	s_lshl_b64 s[0:1], s[40:41], 18
	s_add_u32 s6, s82, s0
	s_addc_u32 s7, s83, s1
	v_readlane_b32 s0, v254, 20
	v_readlane_b32 s1, v254, 21
	s_and_b64 s[0:1], s[0:1], exec
	v_mov_b32_e32 v4, v179
	s_barrier
	s_movk_i32 s0, 0x210
	s_cselect_b32 s63, 0x200, s0
	v_readfirstlane_b32 s5, v4
	s_ashr_i32 s4, s5, 6
	s_and_b32 s1, s4, 1
	v_and_b32_e32 v160, 31, v4
	s_and_b32 s8, s5, 0xffffff80
	s_lshl_b32 s0, s1, 6
	v_or_b32_e32 v0, s8, v160
	v_or_b32_e32 v2, s0, v0
	v_and_b32_e32 v0, 32, v4
	v_mov_b32_e32 v1, v177
	v_ashrrev_i32_e32 v3, 31, v2
	v_lshl_add_u64 v[14:15], s[6:7], 0, v[0:1]
	v_lshlrev_b64 v[6:7], 9, v[2:3]
	v_lshl_add_u64 v[16:17], v[14:15], 0, v[6:7]
	global_load_dwordx4 v[20:23], v[16:17], off
	global_load_dwordx4 v[24:27], v[16:17], off offset:16
	global_load_dwordx4 v[28:31], v[16:17], off offset:64
	global_load_dwordx4 v[32:35], v[16:17], off offset:80
	global_load_dwordx4 v[36:39], v[16:17], off offset:128
	global_load_dwordx4 v[40:43], v[16:17], off offset:144
	global_load_dwordx4 v[44:47], v[16:17], off offset:192
	global_load_dwordx4 v[48:51], v[16:17], off offset:208
	global_load_dwordx4 v[52:55], v[16:17], off offset:256
	global_load_dwordx4 v[56:59], v[16:17], off offset:272
	global_load_dwordx4 v[60:63], v[16:17], off offset:320
	global_load_dwordx4 v[128:131], v[16:17], off offset:336
	global_load_dwordx4 v[132:135], v[16:17], off offset:384
	global_load_dwordx4 v[136:139], v[16:17], off offset:400
	global_load_dwordx4 v[140:143], v[16:17], off offset:448
	global_load_dwordx4 v[144:147], v[16:17], off offset:464
	v_readlane_b32 s6, v254, 5
	s_cmp_ge_i32 s6, s63
	s_waitcnt vmcnt(1)
	v_cvt_pk_bf16_f32 v64, v20, v21
	v_cvt_pk_bf16_f32 v65, v22, v23
	s_waitcnt vmcnt(0)
	v_cvt_pk_bf16_f32 v66, v24, v25
	v_cvt_pk_bf16_f32 v67, v26, v27
	s_waitcnt vmcnt(1)
	v_cvt_pk_bf16_f32 v68, v28, v29
	v_cvt_pk_bf16_f32 v69, v30, v31
	s_waitcnt vmcnt(0)
	v_cvt_pk_bf16_f32 v70, v32, v33
	v_cvt_pk_bf16_f32 v71, v34, v35
	s_waitcnt vmcnt(1)
	v_cvt_pk_bf16_f32 v72, v36, v37
	v_cvt_pk_bf16_f32 v73, v38, v39
	s_waitcnt vmcnt(0)
	v_cvt_pk_bf16_f32 v74, v40, v41
	v_cvt_pk_bf16_f32 v75, v42, v43
	s_waitcnt vmcnt(1)
	v_cvt_pk_bf16_f32 v76, v44, v45
	v_cvt_pk_bf16_f32 v77, v46, v47
	s_waitcnt vmcnt(0)
	v_cvt_pk_bf16_f32 v78, v48, v49
	v_cvt_pk_bf16_f32 v79, v50, v51
	s_waitcnt vmcnt(1)
	v_cvt_pk_bf16_f32 v80, v52, v53
	v_cvt_pk_bf16_f32 v81, v54, v55
	s_waitcnt vmcnt(0)
	v_cvt_pk_bf16_f32 v82, v56, v57
	v_cvt_pk_bf16_f32 v83, v58, v59
	s_waitcnt vmcnt(1)
	v_cvt_pk_bf16_f32 v84, v60, v61
	v_cvt_pk_bf16_f32 v85, v62, v63
	s_waitcnt vmcnt(0)
	v_cvt_pk_bf16_f32 v86, v128, v129
	v_cvt_pk_bf16_f32 v87, v130, v131
	s_waitcnt vmcnt(1)
	v_cvt_pk_bf16_f32 v88, v132, v133
	v_cvt_pk_bf16_f32 v89, v134, v135
	s_waitcnt vmcnt(0)
	v_cvt_pk_bf16_f32 v90, v136, v137
	v_cvt_pk_bf16_f32 v91, v138, v139
	v_or_b32_e32 v16, 32, v2
	v_ashrrev_i32_e32 v17, 31, v16
	v_lshlrev_b64 v[16:17], 9, v[16:17]
	v_lshl_add_u64 v[14:15], v[14:15], 0, v[16:17]
	s_waitcnt vmcnt(1)
	v_cvt_pk_bf16_f32 v92, v140, v141
	v_cvt_pk_bf16_f32 v93, v142, v143
	s_waitcnt vmcnt(0)
	v_cvt_pk_bf16_f32 v94, v144, v145
	v_cvt_pk_bf16_f32 v95, v146, v147
	global_load_dwordx4 v[20:23], v[14:15], off
	global_load_dwordx4 v[24:27], v[14:15], off offset:16
	global_load_dwordx4 v[28:31], v[14:15], off offset:64
	global_load_dwordx4 v[32:35], v[14:15], off offset:80
	global_load_dwordx4 v[36:39], v[14:15], off offset:128
	global_load_dwordx4 v[40:43], v[14:15], off offset:144
	global_load_dwordx4 v[44:47], v[14:15], off offset:192
	global_load_dwordx4 v[48:51], v[14:15], off offset:208
	global_load_dwordx4 v[52:55], v[14:15], off offset:256
	global_load_dwordx4 v[56:59], v[14:15], off offset:272
	global_load_dwordx4 v[60:63], v[14:15], off offset:320
	global_load_dwordx4 v[128:131], v[14:15], off offset:336
	global_load_dwordx4 v[132:135], v[14:15], off offset:384
	global_load_dwordx4 v[136:139], v[14:15], off offset:400
	global_load_dwordx4 v[140:143], v[14:15], off offset:448
	global_load_dwordx4 v[144:147], v[14:15], off offset:464
	s_waitcnt vmcnt(1)
	v_cvt_pk_bf16_f32 v96, v20, v21
	v_cvt_pk_bf16_f32 v97, v22, v23
	s_waitcnt vmcnt(0)
	v_cvt_pk_bf16_f32 v98, v24, v25
	v_cvt_pk_bf16_f32 v99, v26, v27
	s_waitcnt vmcnt(1)
	v_cvt_pk_bf16_f32 v100, v28, v29
	v_cvt_pk_bf16_f32 v101, v30, v31
	s_waitcnt vmcnt(0)
	v_cvt_pk_bf16_f32 v102, v32, v33
	v_cvt_pk_bf16_f32 v103, v34, v35
	s_waitcnt vmcnt(1)
	v_cvt_pk_bf16_f32 v104, v36, v37
	v_cvt_pk_bf16_f32 v105, v38, v39
	s_waitcnt vmcnt(0)
	v_cvt_pk_bf16_f32 v106, v40, v41
	v_cvt_pk_bf16_f32 v107, v42, v43
	s_waitcnt vmcnt(1)
	v_cvt_pk_bf16_f32 v108, v44, v45
	v_cvt_pk_bf16_f32 v109, v46, v47
	s_waitcnt vmcnt(0)
	v_cvt_pk_bf16_f32 v110, v48, v49
	v_cvt_pk_bf16_f32 v111, v50, v51
	s_waitcnt vmcnt(1)
	v_cvt_pk_bf16_f32 v112, v52, v53
	v_cvt_pk_bf16_f32 v113, v54, v55
	s_waitcnt vmcnt(0)
	v_cvt_pk_bf16_f32 v114, v56, v57
	v_cvt_pk_bf16_f32 v115, v58, v59
	s_waitcnt vmcnt(1)
	v_cvt_pk_bf16_f32 v116, v60, v61
	v_cvt_pk_bf16_f32 v117, v62, v63
	s_waitcnt vmcnt(0)
	v_cvt_pk_bf16_f32 v118, v128, v129
	v_cvt_pk_bf16_f32 v119, v130, v131
	s_waitcnt vmcnt(1)
	v_cvt_pk_bf16_f32 v120, v132, v133
	v_cvt_pk_bf16_f32 v121, v134, v135
	s_waitcnt vmcnt(0)
	v_cvt_pk_bf16_f32 v122, v136, v137
	v_cvt_pk_bf16_f32 v123, v138, v139
	s_waitcnt vmcnt(1)
	v_cvt_pk_bf16_f32 v124, v140, v141
	v_cvt_pk_bf16_f32 v125, v142, v143
	s_waitcnt vmcnt(0)
	v_cvt_pk_bf16_f32 v126, v144, v145
	v_cvt_pk_bf16_f32 v127, v146, v147
	s_cbranch_scc1 .LBB0_353
; __device__ __forceinline__ void sgu_units(LAS unsigned char* lds, const bf16* UB, const bf16* GVT, const bf16* GVTc, bf16* MIX, const float* wsgu, const float* bsgu, const float* gsgu, const float* gmix,
;                                           int nchunks, int G, int bid, int tid) {
;     ...
;     for (int L = bid; L < nchunks; L += G) {
;         const int chunk = (L < 512 && (G & 7) == 0) ? (L & 7) * 64 + (L >> 3) : L;
;         const bool isctx = chunk >= 512; const int b = isctx ? (chunk - 512) >> 1 : chunk >> 6, s0 = isctx ? ((chunk - 512) & 1) * 128 : (chunk & 63) * 128;
;         const int ld = isctx ? CTXL : SEQ;
;         const bf16* Gt = (isctx ? GVTc + ((size_t)(b * 256 + hd * 64)) * CTXL : GVT + ((size_t)(b * 256 + hd * 64)) * SEQ) + s0;
;         float sa = 0.f, sb = 0.f;
; #pragma unroll 1
;         for (int d0 = 0; d0 < 64; d0 += 32) { unsigned gv[32];
; #pragma unroll
;             for (int d = 0; d < 32; ++d) gv[d] = *(const unsigned*)(Gt + (size_t)(d0 + d) * ld + 2 * lane);
; #pragma unroll
;             for (int d = 0; d < 32; ++d) { const float x0 = bflo(gv[d]), x1 = bfhi(gv[d]); sa += x0 * x0; sb += x1 * x1; } }
;         LDS_WAIT();
;         rq[2 * lane] = rsqrtf(sa * (1.f / 64.f) + EPSN); rq[2 * lane + 1] = rsqrtf(sb * (1.f / 64.f) + EPSN);
;         LDS_WAIT();
;         f32x16 o[2][2];
; #pragma unroll
;         for (int dt = 0; dt < 2; ++dt)
; #pragma unroll
;             for (int ps = 0; ps < 2; ++ps)
; #pragma unroll
;                 for (int r = 0; r < 16; ++r) o[dt][ps][r] = 0.f;
;         v4u afr[2][8];
; #pragma unroll
;         for (int ks = 0; ks < 8; ++ks)
; #pragma unroll
;             for (int dt = 0; dt < 2; ++dt) afr[dt][ks] = *(const v4u*)(Gt + (size_t)(dt * 32 + c) * ld + ks * 16 + h2 * 8);
;         LAS bf16* utile = (LAS bf16*)(lds + 8192 + wave * 9216);
;         { v4u ut[8];
; #pragma unroll
;           for (int it = 0; it < 8; ++it) ut[it] = *(const v4u*)(UB + ((size_t)chunk * 128 + ph * 64 + it * 8 + (lane >> 3)) * 256 + hd * 64 + (lane & 7) * 8);
; #pragma unroll
;           for (int it = 0; it < 8; ++it) *(LAS v4u*)(utile + (it * 8 + (lane >> 3)) * 72 + (lane & 7) * 8) = ut[it]; }
; #pragma unroll
;         for (int ks = 0; ks < 8; ++ks) {
;             const f32x4 r0 = *(const LAS f32x4*)(rq + ks * 16 + h2 * 8), r1 = *(const LAS f32x4*)(rq + ks * 16 + h2 * 8 + 4);
; #pragma unroll
	s_lshl_b32 s46, s40, 8
	s_lshl_b64 s[6:7], s[46:47], 2
	s_add_u32 s14, s86, s6
	s_addc_u32 s15, s87, s7
	s_lshl_b32 s46, s40, 9
	s_lshl_b64 s[6:7], s[46:47], 2
	s_add_u32 s6, s84, s6
	s_addc_u32 s7, s85, s7
	s_ashr_i32 s5, s5, 1
	s_lshl_b32 s8, s4, 9
	s_and_b32 s10, s5, 0xffffffc0
	s_add_i32 s18, s8, 0
	s_mulk_i32 s4, 0x2200
	s_ashr_i32 s11, s10, 31
	s_add_i32 s28, s10, 0xffff0000
	s_add_i32 s19, s18, s4
	s_lshl_b64 s[8:9], s[10:11], 1
	v_readlane_b32 s4, v253, 5
	s_add_u32 s4, s4, s8
	v_readlane_b32 s5, v253, 6
	s_addc_u32 s5, s5, s9
	s_lshl_b64 s[12:13], s[10:11], 2
	s_add_u32 s14, s14, s12
	s_addc_u32 s15, s15, s13
	s_lshl_b32 s11, s1, 8
	v_readlane_b32 s22, v255, 3
	v_readlane_b32 s23, v255, 4
	s_add_u32 s12, s22, s12
	v_and_b32_e32 v1, 63, v4
	v_bfe_u32 v5, v4, 5, 1
	v_lshlrev_b32_e32 v4, 4, v4
	s_addc_u32 s13, s23, s13
	v_lshl_add_u64 v[192:193], v[2:3], 2, s[6:7]
	v_readlane_b32 s6, v253, 53
	v_lshlrev_b32_e32 v7, 3, v5
	v_lshrrev_b32_e32 v162, 3, v1
	v_and_b32_e32 v176, 0x70, v4
	v_mul_u32_u24_e32 v3, 0x90, v160
	v_readlane_b32 s7, v253, 54
	s_add_u32 s6, s6, s8
	v_lshl_add_u32 v8, v160, 2, 0
	v_lshlrev_b32_e32 v6, 1, v1
	v_lshlrev_b32_e32 v9, 3, v1
	v_lshl_add_u64 v[166:167], s[4:5], 0, v[176:177]
	v_add_u32_e32 v10, s19, v176
	v_cmp_gt_u32_e64 s[4:5], 32, v1
	v_mul_u32_u24_e32 v1, 0x90, v162
	v_lshlrev_b32_e32 v4, 4, v5
	v_mov_b32_e32 v5, v177
	v_add3_u32 v163, s19, v3, v7
	s_addc_u32 s7, s7, s9
	v_or_b32_e32 v164, s0, v162
	s_mov_b32 s1, s47
	v_mov_b32_e32 v161, v177
	v_or_b32_e32 v168, 32, v160
	v_mov_b32_e32 v169, v177
	v_or_b32_e32 v170, 8, v162
	v_or_b32_e32 v172, 16, v162
	v_or_b32_e32 v174, 24, v162
	v_or_b32_e32 v180, 32, v162
	v_or_b32_e32 v186, 40, v162
	v_or_b32_e32 v188, 48, v162
	v_or_b32_e32 v190, 56, v162
	v_lshl_add_u64 v[194:195], s[14:15], 0, v[4:5]
	v_lshl_add_u32 v165, v2, 2, 0
	v_add_u32_e32 v171, 0x1200, v163
	v_lshl_add_u64 v[196:197], s[12:13], 0, v[4:5]
	v_lshl_add_u64 v[198:199], s[6:7], 0, v[176:177]
	v_lshlrev_b32_e32 v176, 1, v6
	v_add_u32_e32 v173, s18, v9
	v_lshlrev_b32_e32 v200, 1, v7
	v_add_u32_e32 v175, s18, v0
	v_add_u32_e32 v187, s11, v8
	v_add_u32_e32 v189, v10, v1
	v_readlane_b32 s11, v254, 5
	s_branch .LBB0_342
